# hand-written grid barrier (last partition releases all partitions directly: one memory round trip less) + W_in: remainder column tile skips the MFMA groups of its unused column half and is scheduled l
# speedup vs baseline: 1.1353x; 1.0259x over previous
.LBB0_6:
	v_readlane_b32 s4, v253, 0
	s_lshl_b32 s2, s4, 4
	s_load_dwordx16 s[48:63], s[0:1], 0x0
	s_add_u32 s0, s0, 0x80
	v_writelane_b32 v253, s2, 4
	s_addc_u32 s1, s1, 0
	v_writelane_b32 v253, s0, 5
	v_lshrrev_b32_e32 v2, 20, v0
	v_lshrrev_b32_e32 v0, 10, v0
	v_writelane_b32 v253, s1, 6
	s_add_u32 s0, s74, 0x13700000
	v_writelane_b32 v253, s0, 7
	s_addc_u32 s0, s75, 0
	v_writelane_b32 v253, s0, 8
	s_add_u32 s0, s74, 0x142b0000
	v_writelane_b32 v253, s0, 9
	s_addc_u32 s0, s75, 0
	v_writelane_b32 v253, s0, 10
	s_add_u32 s0, s74, 0x146f0000
	v_writelane_b32 v253, s0, 11
	s_addc_u32 s0, s75, 0
	v_writelane_b32 v253, s0, 12
	s_add_u32 s0, s74, 0x14750000
	v_writelane_b32 v253, s0, 13
	s_addc_u32 s0, s75, 0
	s_waitcnt lgkmcnt(0)
	s_cmp_lg_u64 s[50:51], 0
	s_cselect_b64 s[82:83], -1, 0
	s_cmp_lg_u64 s[60:61], 0
	s_cselect_b64 s[84:85], -1, 0
	s_cmp_lg_u64 s[62:63], 0
	v_writelane_b32 v253, s0, 14
	s_cselect_b64 s[86:87], -1, 0
	s_add_u32 s0, s74, 0x14790000
	s_addc_u32 s1, s75, 0
	v_writelane_b32 v253, s0, 15
	v_or_b32_e32 v0, v0, v2
	v_mov_b32_e32 v210, 0x358637bd
	v_writelane_b32 v253, s1, 16
	s_add_u32 s0, s74, 0x4401000
	v_writelane_b32 v253, s0, 17
	s_addc_u32 s0, s75, 0
	v_writelane_b32 v253, s0, 18
	s_add_u32 s0, s74, 0x4401180
	v_writelane_b32 v253, s0, 19
	s_addc_u32 s0, s75, 0
	v_writelane_b32 v253, s0, 20
	s_add_u32 s0, s74, 0xea00000
	s_addc_u32 s1, s75, 0
	v_writelane_b32 v253, s0, 21
	v_mbcnt_lo_u32_b32 v2, -1, 0
	v_mbcnt_hi_u32_b32 v221, -1, v2
	v_writelane_b32 v253, s1, 22
	s_add_u32 s0, s74, 0x10200000
	s_addc_u32 s1, s75, 0
	v_writelane_b32 v253, s0, 23
	v_and_b32_e32 v2, 64, v221
	v_mov_b32_e32 v211, 0x3e91f4c4
	v_writelane_b32 v253, s1, 24
	s_add_u32 s0, s74, 0x12680000
	s_addc_u32 s1, s75, 0
	v_writelane_b32 v253, s0, 25
	s_cmpk_lt_i32 s4, 0x200
	v_mov_b32_e32 v212, 0x3c0881c4
	v_writelane_b32 v253, s1, 26
	s_cselect_b64 s[0:1], -1, 0
	v_writelane_b32 v253, s0, 27
	v_mov_b32_e32 v213, 0xbab64f3b
	v_add_u32_e32 v222, 64, v2
	v_writelane_b32 v253, s1, 28
	s_add_u32 s0, s74, 0x4400000
	s_addc_u32 s1, s75, 0
	v_writelane_b32 v253, s0, 29
	s_cmpk_lt_u32 s4, 0x200
	v_xor_b32_e32 v217, 16, v221
	v_writelane_b32 v253, s1, 30
	s_cselect_b64 s[0:1], -1, 0
	v_writelane_b32 v253, s0, 31
	s_lshr_b32 s5, s4, 3
	v_xor_b32_e32 v225, 8, v221
	v_writelane_b32 v253, s1, 32
	s_lshl_b32 s0, s4, 6
	v_writelane_b32 v253, s0, 33
	s_and_b32 s0, s0, 0x1c0
	v_writelane_b32 v253, s0, 34
	s_and_b32 s0, s4, 7
	s_add_u32 s1, s74, 0x14853600
	v_writelane_b32 v253, s1, 35
	s_addc_u32 s1, s75, 0
	v_writelane_b32 v253, s1, 36
	s_lshl_b32 s1, s0, 4
	v_writelane_b32 v253, s1, 37
	s_lshl_b32 s1, s0, 1
	s_cmpk_lt_u32 s7, 0x100
	v_writelane_b32 v253, s1, 38
	s_cselect_b64 s[2:3], -1, 0
	v_writelane_b32 v253, s2, 39
	s_cmpk_gt_u32 s7, 0xff
	v_xor_b32_e32 v226, 4, v221
	v_writelane_b32 v253, s3, 40
	s_cselect_b64 s[2:3], -1, 0
	v_writelane_b32 v253, s2, 41
	s_and_b32 s7, s7, 0xc0
	v_xor_b32_e32 v227, 2, v221
	v_writelane_b32 v253, s3, 42
	s_add_u32 s2, s74, 0x147d0000
	s_addc_u32 s3, s75, 0
	v_writelane_b32 v253, s2, 43
	s_add_u32 s1, s74, 0x11e40000
	v_xor_b32_e32 v228, 1, v221
	v_writelane_b32 v253, s3, 44
	v_writelane_b32 v253, s1, 45
	s_movk_i32 s1, 0x3ff
	v_and_or_b32 v0, v0, s1, v1
	s_addc_u32 s1, s75, 0
	v_writelane_b32 v253, s1, 46
	s_add_u32 s1, s74, 0x11600000
	v_writelane_b32 v253, s1, 47
	s_addc_u32 s1, s75, 0
	s_add_u32 s2, s74, 0x18c53e00
	v_writelane_b32 v253, s1, 48
	s_addc_u32 s3, s75, 0
	v_writelane_b32 v253, s2, 49
	s_cmpk_lt_i32 s4, 0x580
	v_mov_b32_e32 v1, 0
	v_writelane_b32 v253, s3, 50
	s_cselect_b64 s[2:3], -1, 0
	v_writelane_b32 v253, s2, 51
	s_cmpk_lt_u32 s4, 0x580
	s_movk_i32 s33, 0x880
	v_writelane_b32 v253, s3, 52
	s_cselect_b64 s[2:3], -1, 0
	v_writelane_b32 v253, s2, 53
	s_add_u32 s1, s74, 0x14853e00
	s_movk_i32 s34, 0xf500
	v_writelane_b32 v253, s3, 54
	v_writelane_b32 v253, s1, 55
	s_addc_u32 s1, s75, 0
	s_cmp_lt_i32 s8, 0
	v_writelane_b32 v253, s1, 56
	s_cselect_b64 s[2:3], -1, 0
	v_writelane_b32 v253, s2, 57
	s_cmp_eq_u32 s6, 15
	s_movk_i32 s35, 0xb00
	v_writelane_b32 v253, s3, 58
	s_cselect_b64 s[2:3], -1, 0
	v_writelane_b32 v253, s2, 59
	s_cmp_eq_u32 s6, 14
	s_movk_i32 s14, 0x2980
	v_writelane_b32 v253, s3, 60
	s_cselect_b64 s[2:3], -1, 0
	v_writelane_b32 v253, s2, 61
	s_cmp_eq_u32 s6, 13
	s_mov_b32 s15, 0x220000
	v_writelane_b32 v253, s3, 62
	s_cselect_b64 s[2:3], -1, 0
	v_writelane_b32 v253, s2, 63
	s_cmp_eq_u32 s6, 12
	s_mov_b32 s76, 0x30000
	v_writelane_b32 v254, s3, 0
	s_cselect_b64 s[2:3], -1, 0
	v_writelane_b32 v254, s2, 1
	s_cmp_eq_u32 s6, 11
	s_mov_b64 s[26:27], 0x80
	v_writelane_b32 v254, s3, 2
	s_cselect_b64 s[2:3], -1, 0
	v_writelane_b32 v254, s2, 3
	s_cmp_eq_u32 s6, 10
	s_mov_b32 s29, 0
	v_writelane_b32 v254, s3, 4
	s_cselect_b64 s[2:3], -1, 0
	v_writelane_b32 v254, s2, 5
	s_cmp_eq_u32 s6, 9
	s_mov_b64 s[46:47], 0x44080
	v_writelane_b32 v254, s3, 6
	s_cselect_b64 s[2:3], -1, 0
	v_writelane_b32 v254, s2, 7
	s_cmp_eq_u32 s6, 8
	s_mov_b64 s[96:97], 0x100
	v_writelane_b32 v254, s3, 8
	s_cselect_b64 s[2:3], -1, 0
	v_writelane_b32 v254, s2, 9
	s_cmp_eq_u32 s6, 7
	s_mov_b64 s[12:13], 0x44100
	v_writelane_b32 v254, s3, 10
	s_cselect_b64 s[2:3], -1, 0
	v_writelane_b32 v254, s2, 11
	s_cmp_eq_u32 s6, 6
	s_mov_b64 s[16:17], 0x180
	v_writelane_b32 v254, s3, 12
	s_cselect_b64 s[2:3], -1, 0
	v_writelane_b32 v254, s2, 13
	s_cmp_eq_u32 s6, 5
	s_mov_b64 s[80:81], 0x13700180
	v_writelane_b32 v254, s3, 14
	s_cselect_b64 s[2:3], -1, 0
	v_writelane_b32 v254, s2, 15
	s_cmp_eq_u32 s6, 4
	s_mov_b64 s[10:11], 0x13744180
	v_writelane_b32 v254, s3, 16
	s_cselect_b64 s[2:3], -1, 0
	v_writelane_b32 v254, s2, 17
	s_cmp_eq_u32 s6, 3
	s_nop 0
	v_writelane_b32 v254, s3, 18
	s_cselect_b64 s[2:3], -1, 0
	v_writelane_b32 v254, s2, 19
	s_cmp_eq_u32 s6, 2
	s_nop 0
	v_writelane_b32 v254, s3, 20
	s_cselect_b64 s[2:3], -1, 0
	v_writelane_b32 v254, s2, 21
	s_cmp_eq_u32 s6, 1
	s_nop 0
	v_writelane_b32 v254, s3, 22
	s_cselect_b64 s[2:3], -1, 0
	v_writelane_b32 v254, s2, 23
	s_cmp_eq_u32 s6, 0
	s_nop 0
	v_writelane_b32 v254, s3, 24
	s_cselect_b64 s[2:3], -1, 0
	v_writelane_b32 v254, s2, 25
	s_lshl_b32 s1, s6, 6
	s_mov_b32 s6, 0xba2e8ba3
	v_writelane_b32 v254, s3, 26
	s_add_u32 s2, s72, 0x1000
	s_addc_u32 s3, s73, 0
	v_writelane_b32 v254, s2, 27
	s_nop 1
	v_writelane_b32 v254, s3, 28
	s_add_u32 s2, s48, 0x1000
	s_addc_u32 s3, s49, 0
	v_writelane_b32 v254, s2, 29
	s_nop 1
	v_writelane_b32 v254, s3, 30
	s_add_u32 s2, s74, 0xe80
	s_addc_u32 s3, s75, 0
	v_writelane_b32 v254, s2, 31
	s_nop 1
	v_writelane_b32 v254, s3, 32
	s_lshl_b32 s2, s0, 12
	s_lshl_b32 s3, s5, 6
	s_add_i32 s2, s2, s3
	v_writelane_b32 v254, s2, 33
	s_lshl_b32 s2, s5, 1
	v_writelane_b32 v254, s2, 34
	s_lshl_b32 s2, s0, 8
	v_writelane_b32 v254, s2, 35
	v_writelane_b32 v254, s7, 36
	s_sub_i32 s2, s7, 56
	v_writelane_b32 v254, s2, 37
	s_add_u32 s2, s74, 0x12680100
	s_addc_u32 s3, s75, 0
	v_writelane_b32 v254, s2, 38
	s_mov_b32 s7, 0x5d8000
	s_nop 0
	v_writelane_b32 v254, s3, 39
	s_mul_i32 s2, s0, 0xb0
	s_lshl_b32 s0, s0, 9
	v_writelane_b32 v254, s2, 40
	s_add_u32 s2, s74, 0x44a7280
	v_writelane_b32 v254, s0, 41
	s_addc_u32 s3, s75, 0
	v_writelane_b32 v254, s2, 42
	s_nop 1
	v_writelane_b32 v254, s3, 43
	s_add_u32 s2, s74, 0x10214000
	s_addc_u32 s3, s75, 0
	v_writelane_b32 v254, s2, 44
	s_lshl_b32 s0, s1, 2
	s_nop 0
	v_writelane_b32 v254, s3, 45
	v_writelane_b32 v254, s0, 46
	s_lshl_b32 s0, s4, 8
	v_writelane_b32 v254, s0, 47
	v_writelane_b32 v254, s5, 48
	s_lshl_b32 s0, s5, 8
	v_writelane_b32 v254, s0, 49
	s_add_i32 s0, 0, 0x20000
	v_writelane_b32 v254, s0, 50
	s_add_i32 s0, 0, 0x20004
	v_writelane_b32 v254, s0, 51
	s_mov_b32 s0, 0
	v_writelane_b32 v255, s0, 12
	v_cmp_eq_u32_e64 s[0:1], 0, v0
	s_movk_i32 s4, 0x14c0
	s_mov_b32 s3, 0x40c00000
	v_writelane_b32 v254, s0, 52
	s_mov_b32 s2, 0x2e8ba2e8
	s_nop 0
	v_writelane_b32 v254, s1, 53
	v_writelane_b32 v254, s77, 54
	s_branch .LBB0_10

.LBB0_358:
	v_mbcnt_lo_u32_b32 v16, -1, 0
	v_mbcnt_hi_u32_b32 v16, -1, v16
	v_readlane_b32 s0, v254, 40
	v_add_u32_e32 v146, s77, v16
	v_ashrrev_i32_e32 v0, 31, v146
	v_lshrrev_b32_e32 v0, 26, v0
	v_add_u32_e32 v0, v146, v0
	v_ashrrev_i32_e32 v12, 6, v0
	v_bfe_i32 v0, v146, 27, 1
	v_lshlrev_b32_e32 v2, 4, v146
	v_lshrrev_b32_e32 v0, 22, v0
	v_add_u32_e32 v0, v2, v0
	v_and_b32_e32 v0, 0xfffffc00, v0
	v_sub_u32_e32 v0, v2, v0
	v_lshrrev_b32_e32 v3, 4, v0
	v_bitop3_b32 v0, v3, v0, 32 bitop3:0x6c
	v_ashrrev_i32_e32 v4, 31, v0
	s_mul_hi_u32 s1, s0, 0xba2e8ba3
	s_lshr_b32 s1, s1, 3
	s_cmpk_lt_u32 s88, 0xa0
	s_cbranch_scc1 .Lwin_full
	s_sub_i32 s78, s88, 0xa0
	s_mov_b32 s24, 10
	s_branch .Lwin_mapped
.Lwin_full:
	s_and_b32 s0, s88, 31
	s_lshl_b32 s24, s0, 1
	s_and_b32 s24, s24, 31
	s_lshr_b32 s0, s0, 4
	s_sub_i32 s24, s24, s0
	s_add_i32 s24, s24, 1
	s_and_b32 s0, s88, 0xe0
	s_add_i32 s0, s0, s24
	s_mul_hi_u32 s78, s0, 0xcccccccd
	s_lshr_b32 s78, s78, 3
	s_mul_i32 s24, s78, 10
	s_sub_i32 s24, s0, s24
.Lwin_mapped:
	s_add_i32 s78, s78, s1
	s_cmp_eq_u32 s24, 10
	s_cselect_b32 s98, 1, 0
	v_lshrrev_b32_e32 v4, 26, v4
	v_add_u32_e32 v4, v0, v4
	v_lshlrev_b32_e32 v3, 3, v12
	v_ashrrev_i32_e32 v14, 6, v4
	v_and_b32_e32 v4, 0xc0, v4
	v_and_b32_e32 v3, 0x3fffff0, v3
	v_sub_u32_e32 v0, v0, v4
	v_mov_b32_e32 v4, 1
	v_add_u32_e32 v3, v14, v3
	v_lshlrev_b32_e32 v5, 5, v12
	v_ashrrev_i16_sdwa v0, v4, sext(v0) dst_sel:DWORD dst_unused:UNUSED_PAD src0_sel:DWORD src1_sel:BYTE_0
	s_movk_i32 s0, 0x440
	v_add_u32_e32 v147, 0, v2
	s_lshl_b32 s79, s78, 8
	s_lshl_b32 s28, s24, 8
	v_and_b32_e32 v13, 32, v5
	v_bfe_i32 v15, v0, 0, 16
	v_mul_lo_u32 v0, v3, s0
	s_mul_i32 s18, s24, 0x88000
	v_readlane_b32 s8, v254, 61
	v_add_u32_e32 v148, 0x10000, v147
	v_or_b32_e32 v0, v0, v13
	s_mul_hi_u32 s19, s28, 0x880
	s_add_u32 s20, s8, s18
	v_readlane_b32 s9, v254, 63
	v_readfirstlane_b32 s0, v148
	v_add_u32_e32 v149, 0x12000, v147
	v_add_lshl_u32 v0, v0, v15, 1
	s_addc_u32 s21, s9, s19
	s_mov_b32 m0, s0
	v_readfirstlane_b32 s0, v149
	s_mul_i32 s22, s78, 0x88000
	v_readlane_b32 s5, v255, 3
	global_load_lds_dwordx4 v0, s[20:21]
	v_add_u32_e32 v2, 0x22000, v0
	s_mov_b32 m0, s0
	s_mul_hi_u32 s23, s79, 0x880
	s_add_u32 s36, s5, s22
	v_readlane_b32 s38, v254, 60
	v_readfirstlane_b32 s0, v147
	v_add_u32_e32 v151, 0x2000, v147
	global_load_lds_dwordx4 v2, s[20:21]
	s_addc_u32 s37, s38, s23
	s_mov_b32 m0, s0
	v_readfirstlane_b32 s0, v151
	global_load_lds_dwordx4 v0, s[36:37]
	s_mov_b32 m0, s0
	s_mul_i32 s0, s24, 0x44000
	s_mov_b32 s1, s29
	s_lshl_b64 s[0:1], s[0:1], 1
	s_add_u32 s25, s8, s0
	s_addc_u32 s30, s9, s1
	v_add_u32_e32 v152, 0x14000, v147
	s_add_u32 s8, s25, 0x44000
	v_readfirstlane_b32 s31, v152
	v_add_u32_e32 v153, 0x16000, v147
	global_load_lds_dwordx4 v2, s[36:37]
	s_addc_u32 s9, s30, 0
	s_mov_b32 m0, s31
	v_readfirstlane_b32 s31, v153
	global_load_lds_dwordx4 v0, s[8:9]
	s_mov_b32 m0, s31
	v_add_u32_e32 v154, 0x4000, v147
	global_load_lds_dwordx4 v2, s[8:9]
	s_or_b32 s8, s79, 0x80
	s_mul_hi_u32 s9, s8, 0x880
	s_mulk_i32 s8, 0x880
	s_add_u32 s8, s5, s8
	v_readfirstlane_b32 s31, v154
	v_add_u32_e32 v155, 0x6000, v147
	s_addc_u32 s9, s38, s9
	s_mov_b32 m0, s31
	v_readfirstlane_b32 s31, v155
	global_load_lds_dwordx4 v0, s[8:9]
	s_mov_b32 m0, s31
	v_ashrrev_i32_e32 v17, 8, v146
	global_load_lds_dwordx4 v2, s[8:9]
	v_mov_b32_e32 v3, v1
	v_mov_b32_e32 v229, 0xbab64f3b
	v_mov_b32_e32 v223, 0x3c0881c4
	v_mov_b32_e32 v220, 0x3e91f4c4
	v_lshl_add_u64 v[10:11], s[20:21], 0, v[0:1]
	v_lshl_add_u64 v[8:9], s[20:21], 0, v[2:3]
	v_lshl_add_u64 v[6:7], s[36:37], 0, v[0:1]
	v_lshl_add_u64 v[4:5], s[36:37], 0, v[2:3]
	v_cmp_eq_u32_e32 vcc, 1, v17
	s_and_saveexec_b64 s[20:21], vcc
	s_cbranch_execz .LBB0_360
	s_barrier

.LBB0_361:
	ds_read_b128 v[164:167], v150
	ds_read_b128 v[168:171], v150 offset:1024
	ds_read_b128 v[172:175], v150 offset:2048
	ds_read_b128 v[176:179], v150 offset:3072
	v_add_u32_e32 v162, 0xc000, v147
	v_lshl_add_u64 v[224:225], s[74:75], 0, v[138:139]
	v_readfirstlane_b32 s1, v162
	v_add_u32_e32 v163, 0xe000, v147
	v_lshl_add_u64 v[212:213], v[224:225], 0, s[46:47]
	s_mov_b32 m0, s1
	v_lshl_add_u64 v[238:239], s[74:75], 0, v[140:141]
	v_readfirstlane_b32 s1, v163
	ds_read_b128 v[180:183], v0
	ds_read_b128 v[184:187], v0 offset:1024
	ds_read_b128 v[188:191], v0 offset:2048
	ds_read_b128 v[192:195], v0 offset:3072
	ds_read_b128 v[196:199], v0 offset:4096
	ds_read_b128 v[200:203], v0 offset:5120
	ds_read_b128 v[204:207], v0 offset:6144
	ds_read_b128 v[208:211], v0 offset:7168
	global_load_lds_dwordx4 v[212:213], off
	v_lshl_add_u64 v[212:213], v[238:239], 0, s[46:47]
	s_mov_b32 m0, s1
	s_nop 0
	global_load_lds_dwordx4 v[212:213], off
	s_waitcnt lgkmcnt(8)
	s_barrier
	s_waitcnt lgkmcnt(0)
	s_setprio 1
	s_waitcnt lgkmcnt(0)
	v_mfma_f32_16x16x32_bf16 v[126:129], v[164:167], v[180:183], v[126:129]
	v_mfma_f32_16x16x32_bf16 v[122:125], v[172:175], v[180:183], v[122:125]
	v_mfma_f32_16x16x32_bf16 v[118:121], v[164:167], v[188:191], v[118:121]
	v_mfma_f32_16x16x32_bf16 v[114:117], v[172:175], v[188:191], v[114:117]
	v_mfma_f32_16x16x32_bf16 v[110:113], v[164:167], v[196:199], v[110:113]
	v_mfma_f32_16x16x32_bf16 v[106:109], v[172:175], v[196:199], v[106:109]
	v_mfma_f32_16x16x32_bf16 v[102:105], v[164:167], v[204:207], v[102:105]
	v_mfma_f32_16x16x32_bf16 v[98:101], v[172:175], v[204:207], v[98:101]
	v_mfma_f32_16x16x32_bf16 v[126:129], v[168:171], v[184:187], v[126:129]
	v_mfma_f32_16x16x32_bf16 v[122:125], v[176:179], v[184:187], v[122:125]
	v_mfma_f32_16x16x32_bf16 v[118:121], v[168:171], v[192:195], v[118:121]
	v_mfma_f32_16x16x32_bf16 v[114:117], v[176:179], v[192:195], v[114:117]
	v_mfma_f32_16x16x32_bf16 v[110:113], v[168:171], v[200:203], v[110:113]
	v_mfma_f32_16x16x32_bf16 v[106:109], v[176:179], v[200:203], v[106:109]
	v_mfma_f32_16x16x32_bf16 v[102:105], v[168:171], v[208:211], v[102:105]
	v_mfma_f32_16x16x32_bf16 v[98:101], v[176:179], v[208:211], v[98:101]
	s_setprio 0
	s_barrier
	v_lshl_add_u64 v[240:241], s[74:75], 0, v[134:135]
	v_readfirstlane_b32 s1, v148
	v_lshl_add_u64 v[242:243], v[240:241], 0, s[8:9]
	s_mov_b32 m0, s1
	ds_read_b128 v[212:215], v150 offset:16384
	ds_read_b128 v[216:219], v150 offset:17408
	ds_read_b128 v[230:233], v150 offset:18432
	ds_read_b128 v[234:237], v150 offset:19456
	global_load_lds_dwordx4 v[242:243], off
	v_lshl_add_u64 v[242:243], s[74:75], 0, v[136:137]
	v_readfirstlane_b32 s1, v149
	v_lshl_add_u64 v[244:245], v[242:243], 0, s[8:9]
	s_mov_b32 m0, s1
	s_nop 0
	global_load_lds_dwordx4 v[244:245], off
	s_barrier
	s_waitcnt lgkmcnt(0)
	s_setprio 1
	s_waitcnt lgkmcnt(0)
	s_cmp_lg_u32 s98, 0
	s_cbranch_scc1 .Lwin_skip7
	v_mfma_f32_16x16x32_bf16 v[94:97], v[212:215], v[180:183], v[94:97]
	v_mfma_f32_16x16x32_bf16 v[90:93], v[230:233], v[180:183], v[90:93]
	v_mfma_f32_16x16x32_bf16 v[86:89], v[212:215], v[188:191], v[86:89]
	v_mfma_f32_16x16x32_bf16 v[82:85], v[230:233], v[188:191], v[82:85]
	v_mfma_f32_16x16x32_bf16 v[78:81], v[212:215], v[196:199], v[78:81]
	v_mfma_f32_16x16x32_bf16 v[74:77], v[230:233], v[196:199], v[74:77]
	v_mfma_f32_16x16x32_bf16 v[70:73], v[212:215], v[204:207], v[70:73]
	v_mfma_f32_16x16x32_bf16 v[66:69], v[230:233], v[204:207], v[66:69]
	v_mfma_f32_16x16x32_bf16 v[94:97], v[216:219], v[184:187], v[94:97]
	v_mfma_f32_16x16x32_bf16 v[90:93], v[234:237], v[184:187], v[90:93]
	v_mfma_f32_16x16x32_bf16 v[86:89], v[216:219], v[192:195], v[86:89]
	v_mfma_f32_16x16x32_bf16 v[82:85], v[234:237], v[192:195], v[82:85]
	v_mfma_f32_16x16x32_bf16 v[78:81], v[216:219], v[200:203], v[78:81]
	v_mfma_f32_16x16x32_bf16 v[74:77], v[234:237], v[200:203], v[74:77]
	v_mfma_f32_16x16x32_bf16 v[70:73], v[216:219], v[208:211], v[70:73]
	v_mfma_f32_16x16x32_bf16 v[66:69], v[234:237], v[208:211], v[66:69]
.Lwin_skip7:
	s_setprio 0
	v_readfirstlane_b32 s1, v147
	v_lshl_add_u64 v[244:245], v[224:225], 0, s[96:97]
	s_mov_b32 m0, s1
	v_readfirstlane_b32 s1, v151
	s_barrier
	ds_read_b128 v[180:183], v0 offset:16384
	ds_read_b128 v[184:187], v0 offset:17408
	ds_read_b128 v[188:191], v0 offset:18432
	ds_read_b128 v[192:195], v0 offset:19456
	ds_read_b128 v[196:199], v0 offset:20480
	ds_read_b128 v[200:203], v0 offset:21504
	ds_read_b128 v[204:207], v0 offset:22528
	ds_read_b128 v[208:211], v0 offset:23552
	global_load_lds_dwordx4 v[244:245], off
	v_lshl_add_u64 v[244:245], v[238:239], 0, s[96:97]
	s_mov_b32 m0, s1
	s_nop 0
	global_load_lds_dwordx4 v[244:245], off
	s_barrier
	s_waitcnt lgkmcnt(0)
	s_setprio 1
	s_waitcnt lgkmcnt(0)
	v_mfma_f32_16x16x32_bf16 v[62:65], v[164:167], v[180:183], v[62:65]
	v_mfma_f32_16x16x32_bf16 v[58:61], v[172:175], v[180:183], v[58:61]
	v_mfma_f32_16x16x32_bf16 v[54:57], v[164:167], v[188:191], v[54:57]
	v_mfma_f32_16x16x32_bf16 v[50:53], v[172:175], v[188:191], v[50:53]
	v_mfma_f32_16x16x32_bf16 v[46:49], v[164:167], v[196:199], v[46:49]
	v_mfma_f32_16x16x32_bf16 v[42:45], v[172:175], v[196:199], v[42:45]
	v_mfma_f32_16x16x32_bf16 v[38:41], v[164:167], v[204:207], v[38:41]
	v_mfma_f32_16x16x32_bf16 v[34:37], v[172:175], v[204:207], v[34:37]
	v_mfma_f32_16x16x32_bf16 v[62:65], v[168:171], v[184:187], v[62:65]
	v_mfma_f32_16x16x32_bf16 v[58:61], v[176:179], v[184:187], v[58:61]
	v_mfma_f32_16x16x32_bf16 v[54:57], v[168:171], v[192:195], v[54:57]
	v_mfma_f32_16x16x32_bf16 v[50:53], v[176:179], v[192:195], v[50:53]
	v_mfma_f32_16x16x32_bf16 v[46:49], v[168:171], v[200:203], v[46:49]
	v_mfma_f32_16x16x32_bf16 v[42:45], v[176:179], v[200:203], v[42:45]
	v_mfma_f32_16x16x32_bf16 v[38:41], v[168:171], v[208:211], v[38:41]
	v_mfma_f32_16x16x32_bf16 v[34:37], v[176:179], v[208:211], v[34:37]
	s_setprio 0
	s_barrier
	v_lshl_add_u64 v[244:245], s[74:75], 0, v[142:143]
	v_readfirstlane_b32 s1, v152
	v_lshl_add_u64 v[164:165], v[244:245], 0, s[18:19]
	s_mov_b32 m0, s1
	v_lshl_add_u64 v[246:247], s[74:75], 0, v[144:145]
	v_readfirstlane_b32 s1, v153
	global_load_lds_dwordx4 v[164:165], off
	v_lshl_add_u64 v[164:165], v[246:247], 0, s[18:19]
	s_mov_b32 m0, s1
	s_nop 0
	global_load_lds_dwordx4 v[164:165], off
	s_waitcnt vmcnt(6)
	s_barrier
	s_setprio 1
	s_cmp_lg_u32 s98, 0
	s_cbranch_scc1 .Lwin_skip6
	v_mfma_f32_16x16x32_bf16 v[30:33], v[212:215], v[180:183], v[30:33]
	v_mfma_f32_16x16x32_bf16 v[26:29], v[230:233], v[180:183], v[26:29]
	v_mfma_f32_16x16x32_bf16 v[22:25], v[212:215], v[188:191], v[22:25]
	v_mfma_f32_16x16x32_bf16 v[18:21], v[230:233], v[188:191], v[18:21]
	v_mfma_f32_16x16x32_bf16 v[14:17], v[212:215], v[196:199], v[14:17]
	v_mfma_f32_16x16x32_bf16 v[10:13], v[230:233], v[196:199], v[10:13]
	v_mfma_f32_16x16x32_bf16 v[6:9], v[212:215], v[204:207], v[6:9]
	v_mfma_f32_16x16x32_bf16 v[2:5], v[230:233], v[204:207], v[2:5]
	v_mfma_f32_16x16x32_bf16 v[30:33], v[216:219], v[184:187], v[30:33]
	v_mfma_f32_16x16x32_bf16 v[26:29], v[234:237], v[184:187], v[26:29]
	v_mfma_f32_16x16x32_bf16 v[22:25], v[216:219], v[192:195], v[22:25]
	v_mfma_f32_16x16x32_bf16 v[18:21], v[234:237], v[192:195], v[18:21]
	v_mfma_f32_16x16x32_bf16 v[14:17], v[216:219], v[200:203], v[14:17]
	v_mfma_f32_16x16x32_bf16 v[10:13], v[234:237], v[200:203], v[10:13]
	v_mfma_f32_16x16x32_bf16 v[6:9], v[216:219], v[208:211], v[6:9]
	v_mfma_f32_16x16x32_bf16 v[2:5], v[234:237], v[208:211], v[2:5]
.Lwin_skip6:
	s_setprio 0
	s_barrier
	ds_read_b128 v[164:167], v150 offset:32768
	ds_read_b128 v[168:171], v150 offset:33792
	ds_read_b128 v[172:175], v150 offset:34816
	ds_read_b128 v[176:179], v150 offset:35840
	v_readfirstlane_b32 s1, v154
	v_lshl_add_u64 v[212:213], v[224:225], 0, s[12:13]
	s_mov_b32 m0, s1
	v_readfirstlane_b32 s1, v155
	ds_read_b128 v[180:183], v0 offset:32768
	ds_read_b128 v[184:187], v0 offset:33792
	ds_read_b128 v[188:191], v0 offset:34816
	ds_read_b128 v[192:195], v0 offset:35840
	ds_read_b128 v[196:199], v0 offset:36864
	ds_read_b128 v[200:203], v0 offset:37888
	ds_read_b128 v[204:207], v0 offset:38912
	ds_read_b128 v[208:211], v0 offset:39936
	global_load_lds_dwordx4 v[212:213], off
	v_lshl_add_u64 v[212:213], v[238:239], 0, s[12:13]
	s_mov_b32 m0, s1
	s_nop 0
	global_load_lds_dwordx4 v[212:213], off
	s_waitcnt lgkmcnt(8)
	s_barrier
	s_waitcnt lgkmcnt(0)
	s_setprio 1
	s_waitcnt lgkmcnt(0)
	v_mfma_f32_16x16x32_bf16 v[126:129], v[164:167], v[180:183], v[126:129]
	v_mfma_f32_16x16x32_bf16 v[122:125], v[172:175], v[180:183], v[122:125]
	v_mfma_f32_16x16x32_bf16 v[118:121], v[164:167], v[188:191], v[118:121]
	v_mfma_f32_16x16x32_bf16 v[114:117], v[172:175], v[188:191], v[114:117]
	v_mfma_f32_16x16x32_bf16 v[110:113], v[164:167], v[196:199], v[110:113]
	v_mfma_f32_16x16x32_bf16 v[106:109], v[172:175], v[196:199], v[106:109]
	v_mfma_f32_16x16x32_bf16 v[102:105], v[164:167], v[204:207], v[102:105]
	v_mfma_f32_16x16x32_bf16 v[98:101], v[172:175], v[204:207], v[98:101]
	v_mfma_f32_16x16x32_bf16 v[126:129], v[168:171], v[184:187], v[126:129]
	v_mfma_f32_16x16x32_bf16 v[122:125], v[176:179], v[184:187], v[122:125]
	v_mfma_f32_16x16x32_bf16 v[118:121], v[168:171], v[192:195], v[118:121]
	v_mfma_f32_16x16x32_bf16 v[114:117], v[176:179], v[192:195], v[114:117]
	v_mfma_f32_16x16x32_bf16 v[110:113], v[168:171], v[200:203], v[110:113]
	v_mfma_f32_16x16x32_bf16 v[106:109], v[176:179], v[200:203], v[106:109]
	v_mfma_f32_16x16x32_bf16 v[102:105], v[168:171], v[208:211], v[102:105]
	v_mfma_f32_16x16x32_bf16 v[98:101], v[176:179], v[208:211], v[98:101]
	s_setprio 0
	s_barrier
	v_readfirstlane_b32 s1, v156
	v_lshl_add_u64 v[240:241], v[240:241], 0, s[80:81]
	s_mov_b32 m0, s1
	v_readfirstlane_b32 s1, v157
	ds_read_b128 v[212:215], v150 offset:49152
	ds_read_b128 v[216:219], v150 offset:50176
	ds_read_b128 v[230:233], v150 offset:51200
	ds_read_b128 v[234:237], v150 offset:52224
	global_load_lds_dwordx4 v[240:241], off
	v_lshl_add_u64 v[240:241], v[242:243], 0, s[80:81]
	s_mov_b32 m0, s1
	s_nop 0
	global_load_lds_dwordx4 v[240:241], off
	s_barrier
	s_waitcnt lgkmcnt(0)
	s_setprio 1
	s_waitcnt lgkmcnt(0)
	s_cmp_lg_u32 s98, 0
	s_cbranch_scc1 .Lwin_skip5
	v_mfma_f32_16x16x32_bf16 v[94:97], v[212:215], v[180:183], v[94:97]
	v_mfma_f32_16x16x32_bf16 v[90:93], v[230:233], v[180:183], v[90:93]
	v_mfma_f32_16x16x32_bf16 v[86:89], v[212:215], v[188:191], v[86:89]
	v_mfma_f32_16x16x32_bf16 v[82:85], v[230:233], v[188:191], v[82:85]
	v_mfma_f32_16x16x32_bf16 v[78:81], v[212:215], v[196:199], v[78:81]
	v_mfma_f32_16x16x32_bf16 v[74:77], v[230:233], v[196:199], v[74:77]
	v_mfma_f32_16x16x32_bf16 v[70:73], v[212:215], v[204:207], v[70:73]
	v_mfma_f32_16x16x32_bf16 v[66:69], v[230:233], v[204:207], v[66:69]
	v_mfma_f32_16x16x32_bf16 v[94:97], v[216:219], v[184:187], v[94:97]
	v_mfma_f32_16x16x32_bf16 v[90:93], v[234:237], v[184:187], v[90:93]
	v_mfma_f32_16x16x32_bf16 v[86:89], v[216:219], v[192:195], v[86:89]
	v_mfma_f32_16x16x32_bf16 v[82:85], v[234:237], v[192:195], v[82:85]
	v_mfma_f32_16x16x32_bf16 v[78:81], v[216:219], v[200:203], v[78:81]
	v_mfma_f32_16x16x32_bf16 v[74:77], v[234:237], v[200:203], v[74:77]
	v_mfma_f32_16x16x32_bf16 v[70:73], v[216:219], v[208:211], v[70:73]
	v_mfma_f32_16x16x32_bf16 v[66:69], v[234:237], v[208:211], v[66:69]
.Lwin_skip5:
	s_setprio 0
	v_readfirstlane_b32 s1, v158
	v_lshl_add_u64 v[224:225], v[224:225], 0, s[16:17]
	s_mov_b32 m0, s1
	v_readfirstlane_b32 s1, v159
	s_barrier
	ds_read_b128 v[180:183], v0 offset:49152
	ds_read_b128 v[184:187], v0 offset:50176
	ds_read_b128 v[188:191], v0 offset:51200
	ds_read_b128 v[192:195], v0 offset:52224
	ds_read_b128 v[196:199], v0 offset:53248
	ds_read_b128 v[200:203], v0 offset:54272
	ds_read_b128 v[204:207], v0 offset:55296
	ds_read_b128 v[208:211], v0 offset:56320
	global_load_lds_dwordx4 v[224:225], off
	v_lshl_add_u64 v[224:225], v[238:239], 0, s[16:17]
	s_mov_b32 m0, s1
	s_nop 0
	global_load_lds_dwordx4 v[224:225], off
	s_barrier
	s_waitcnt lgkmcnt(0)
	s_setprio 1
	s_waitcnt lgkmcnt(0)
	v_mfma_f32_16x16x32_bf16 v[62:65], v[164:167], v[180:183], v[62:65]
	v_mfma_f32_16x16x32_bf16 v[58:61], v[172:175], v[180:183], v[58:61]
	v_mfma_f32_16x16x32_bf16 v[54:57], v[164:167], v[188:191], v[54:57]
	v_mfma_f32_16x16x32_bf16 v[50:53], v[172:175], v[188:191], v[50:53]
	v_mfma_f32_16x16x32_bf16 v[46:49], v[164:167], v[196:199], v[46:49]
	v_mfma_f32_16x16x32_bf16 v[42:45], v[172:175], v[196:199], v[42:45]
	v_mfma_f32_16x16x32_bf16 v[38:41], v[164:167], v[204:207], v[38:41]
	v_mfma_f32_16x16x32_bf16 v[34:37], v[172:175], v[204:207], v[34:37]
	v_mfma_f32_16x16x32_bf16 v[62:65], v[168:171], v[184:187], v[62:65]
	v_mfma_f32_16x16x32_bf16 v[58:61], v[176:179], v[184:187], v[58:61]
	v_mfma_f32_16x16x32_bf16 v[54:57], v[168:171], v[192:195], v[54:57]
	v_mfma_f32_16x16x32_bf16 v[50:53], v[176:179], v[192:195], v[50:53]
	v_mfma_f32_16x16x32_bf16 v[46:49], v[168:171], v[200:203], v[46:49]
	v_mfma_f32_16x16x32_bf16 v[42:45], v[176:179], v[200:203], v[42:45]
	v_mfma_f32_16x16x32_bf16 v[38:41], v[168:171], v[208:211], v[38:41]
	v_mfma_f32_16x16x32_bf16 v[34:37], v[176:179], v[208:211], v[34:37]
	s_setprio 0
	s_barrier
	v_readfirstlane_b32 s1, v160
	v_lshl_add_u64 v[164:165], v[244:245], 0, s[10:11]
	s_mov_b32 m0, s1
	v_readfirstlane_b32 s1, v161
	global_load_lds_dwordx4 v[164:165], off
	v_lshl_add_u64 v[164:165], v[246:247], 0, s[10:11]
	s_mov_b32 m0, s1
	s_nop 0
	global_load_lds_dwordx4 v[164:165], off
	s_waitcnt vmcnt(6)
	s_barrier
	s_setprio 1
	s_cmp_lg_u32 s98, 0
	s_cbranch_scc1 .Lwin_skip4
	v_mfma_f32_16x16x32_bf16 v[30:33], v[212:215], v[180:183], v[30:33]
	v_mfma_f32_16x16x32_bf16 v[26:29], v[230:233], v[180:183], v[26:29]
	v_mfma_f32_16x16x32_bf16 v[22:25], v[212:215], v[188:191], v[22:25]
	v_mfma_f32_16x16x32_bf16 v[18:21], v[230:233], v[188:191], v[18:21]
	v_mfma_f32_16x16x32_bf16 v[14:17], v[212:215], v[196:199], v[14:17]
	v_mfma_f32_16x16x32_bf16 v[10:13], v[230:233], v[196:199], v[10:13]
	v_mfma_f32_16x16x32_bf16 v[6:9], v[212:215], v[204:207], v[6:9]
	v_mfma_f32_16x16x32_bf16 v[2:5], v[230:233], v[204:207], v[2:5]
	v_mfma_f32_16x16x32_bf16 v[30:33], v[216:219], v[184:187], v[30:33]
	v_mfma_f32_16x16x32_bf16 v[26:29], v[234:237], v[184:187], v[26:29]
	v_mfma_f32_16x16x32_bf16 v[22:25], v[216:219], v[192:195], v[22:25]
	v_mfma_f32_16x16x32_bf16 v[18:21], v[234:237], v[192:195], v[18:21]
	v_mfma_f32_16x16x32_bf16 v[14:17], v[216:219], v[200:203], v[14:17]
	v_mfma_f32_16x16x32_bf16 v[10:13], v[234:237], v[200:203], v[10:13]
	v_mfma_f32_16x16x32_bf16 v[6:9], v[216:219], v[208:211], v[6:9]
	v_mfma_f32_16x16x32_bf16 v[2:5], v[234:237], v[208:211], v[2:5]
.Lwin_skip4:
	s_setprio 0
	s_add_i32 s0, s0, 2
	v_lshl_add_u64 v[134:135], v[134:135], 0, s[96:97]
	v_lshl_add_u64 v[136:137], v[136:137], 0, s[96:97]
	v_lshl_add_u64 v[138:139], v[138:139], 0, s[96:97]
	v_lshl_add_u64 v[140:141], v[140:141], 0, s[96:97]
	v_lshl_add_u64 v[142:143], v[142:143], 0, s[96:97]
	s_cmp_lt_u32 s0, 12
	v_lshl_add_u64 v[144:145], v[144:145], 0, s[96:97]
	s_barrier
	s_cbranch_scc1 .LBB0_361
	s_mov_b64 s[8:9], 0x780
	v_readfirstlane_b32 s0, v162
	v_lshl_add_u64 v[132:133], v[132:133], 0, s[8:9]
	s_mov_b32 m0, s0
	v_readfirstlane_b32 s0, v163
	ds_read_b128 v[134:137], v150
	ds_read_b128 v[138:141], v150 offset:1024
	ds_read_b128 v[142:145], v150 offset:2048
	ds_read_b128 v[152:155], v150 offset:3072
	ds_read_b128 v[156:159], v0
	ds_read_b128 v[164:167], v0 offset:1024
	ds_read_b128 v[168:171], v0 offset:2048
	ds_read_b128 v[172:175], v0 offset:3072
	ds_read_b128 v[176:179], v0 offset:4096
	ds_read_b128 v[180:183], v0 offset:5120
	ds_read_b128 v[184:187], v0 offset:6144
	ds_read_b128 v[188:191], v0 offset:7168
	global_load_lds_dwordx4 v[132:133], off
	v_lshl_add_u64 v[130:131], v[130:131], 0, s[8:9]
	s_mov_b32 m0, s0
	s_nop 0
	global_load_lds_dwordx4 v[130:131], off
	s_barrier
	s_waitcnt lgkmcnt(0)
	s_setprio 1
	s_waitcnt lgkmcnt(0)
	v_mfma_f32_16x16x32_bf16 v[126:129], v[134:137], v[156:159], v[126:129]
	v_mfma_f32_16x16x32_bf16 v[122:125], v[142:145], v[156:159], v[122:125]
	v_mfma_f32_16x16x32_bf16 v[118:121], v[134:137], v[168:171], v[118:121]
	v_mfma_f32_16x16x32_bf16 v[114:117], v[142:145], v[168:171], v[114:117]
	v_mfma_f32_16x16x32_bf16 v[110:113], v[134:137], v[176:179], v[110:113]
	v_mfma_f32_16x16x32_bf16 v[106:109], v[142:145], v[176:179], v[106:109]
	v_mfma_f32_16x16x32_bf16 v[102:105], v[134:137], v[184:187], v[102:105]
	v_mfma_f32_16x16x32_bf16 v[98:101], v[142:145], v[184:187], v[98:101]
	v_mfma_f32_16x16x32_bf16 v[126:129], v[138:141], v[164:167], v[126:129]
	v_mfma_f32_16x16x32_bf16 v[122:125], v[152:155], v[164:167], v[122:125]
	v_mfma_f32_16x16x32_bf16 v[118:121], v[138:141], v[172:175], v[118:121]
	v_mfma_f32_16x16x32_bf16 v[114:117], v[152:155], v[172:175], v[114:117]
	v_mfma_f32_16x16x32_bf16 v[110:113], v[138:141], v[180:183], v[110:113]
	v_mfma_f32_16x16x32_bf16 v[106:109], v[152:155], v[180:183], v[106:109]
	v_mfma_f32_16x16x32_bf16 v[102:105], v[138:141], v[188:191], v[102:105]
	v_mfma_f32_16x16x32_bf16 v[98:101], v[152:155], v[188:191], v[98:101]
	s_setprio 0
	s_barrier
	ds_read_b128 v[130:133], v150 offset:16384
	ds_read_b128 v[160:163], v150 offset:17408
	ds_read_b128 v[192:195], v150 offset:18432
	ds_read_b128 v[196:199], v150 offset:19456
	s_barrier
	s_waitcnt lgkmcnt(0)
	s_setprio 1
	s_waitcnt lgkmcnt(0)
	s_cmp_lg_u32 s98, 0
	s_cbranch_scc1 .Lwin_skip3
	v_mfma_f32_16x16x32_bf16 v[94:97], v[130:133], v[156:159], v[94:97]
	v_mfma_f32_16x16x32_bf16 v[90:93], v[192:195], v[156:159], v[90:93]
	v_mfma_f32_16x16x32_bf16 v[86:89], v[130:133], v[168:171], v[86:89]
	v_mfma_f32_16x16x32_bf16 v[82:85], v[192:195], v[168:171], v[82:85]
	v_mfma_f32_16x16x32_bf16 v[78:81], v[130:133], v[176:179], v[78:81]
	v_mfma_f32_16x16x32_bf16 v[74:77], v[192:195], v[176:179], v[74:77]
	v_mfma_f32_16x16x32_bf16 v[70:73], v[130:133], v[184:187], v[70:73]
	v_mfma_f32_16x16x32_bf16 v[66:69], v[192:195], v[184:187], v[66:69]
	v_mfma_f32_16x16x32_bf16 v[94:97], v[160:163], v[164:167], v[94:97]
	v_mfma_f32_16x16x32_bf16 v[90:93], v[196:199], v[164:167], v[90:93]
	v_mfma_f32_16x16x32_bf16 v[86:89], v[160:163], v[172:175], v[86:89]
	v_mfma_f32_16x16x32_bf16 v[82:85], v[196:199], v[172:175], v[82:85]
	v_mfma_f32_16x16x32_bf16 v[78:81], v[160:163], v[180:183], v[78:81]
	v_mfma_f32_16x16x32_bf16 v[74:77], v[196:199], v[180:183], v[74:77]
	v_mfma_f32_16x16x32_bf16 v[70:73], v[160:163], v[188:191], v[70:73]
	v_mfma_f32_16x16x32_bf16 v[66:69], v[196:199], v[188:191], v[66:69]
.Lwin_skip3:
	s_setprio 0
	s_barrier
	ds_read_b128 v[156:159], v0 offset:16384
	ds_read_b128 v[164:167], v0 offset:17408
	ds_read_b128 v[168:171], v0 offset:18432
	ds_read_b128 v[172:175], v0 offset:19456
	ds_read_b128 v[176:179], v0 offset:20480
	ds_read_b128 v[180:183], v0 offset:21504
	ds_read_b128 v[184:187], v0 offset:22528
	ds_read_b128 v[188:191], v0 offset:23552
	s_waitcnt vmcnt(4)
	s_barrier
	s_waitcnt lgkmcnt(0)
	s_setprio 1
	s_waitcnt lgkmcnt(0)
	v_mfma_f32_16x16x32_bf16 v[62:65], v[134:137], v[156:159], v[62:65]
	v_mfma_f32_16x16x32_bf16 v[58:61], v[142:145], v[156:159], v[58:61]
	v_mfma_f32_16x16x32_bf16 v[54:57], v[134:137], v[168:171], v[54:57]
	v_mfma_f32_16x16x32_bf16 v[50:53], v[142:145], v[168:171], v[50:53]
	v_mfma_f32_16x16x32_bf16 v[46:49], v[134:137], v[176:179], v[46:49]
	v_mfma_f32_16x16x32_bf16 v[42:45], v[142:145], v[176:179], v[42:45]
	v_mfma_f32_16x16x32_bf16 v[38:41], v[134:137], v[184:187], v[38:41]
	v_mfma_f32_16x16x32_bf16 v[34:37], v[142:145], v[184:187], v[34:37]
	v_mfma_f32_16x16x32_bf16 v[62:65], v[138:141], v[164:167], v[62:65]
	v_mfma_f32_16x16x32_bf16 v[58:61], v[152:155], v[164:167], v[58:61]
	v_mfma_f32_16x16x32_bf16 v[54:57], v[138:141], v[172:175], v[54:57]
	v_mfma_f32_16x16x32_bf16 v[50:53], v[152:155], v[172:175], v[50:53]
	v_mfma_f32_16x16x32_bf16 v[46:49], v[138:141], v[180:183], v[46:49]
	v_mfma_f32_16x16x32_bf16 v[42:45], v[152:155], v[180:183], v[42:45]
	v_mfma_f32_16x16x32_bf16 v[38:41], v[138:141], v[188:191], v[38:41]
	v_mfma_f32_16x16x32_bf16 v[34:37], v[152:155], v[188:191], v[34:37]
	s_setprio 0
	s_setprio 1
	s_cmp_lg_u32 s98, 0
	s_cbranch_scc1 .Lwin_skip2
	v_mfma_f32_16x16x32_bf16 v[30:33], v[130:133], v[156:159], v[30:33]
	v_mfma_f32_16x16x32_bf16 v[26:29], v[192:195], v[156:159], v[26:29]
	v_mfma_f32_16x16x32_bf16 v[22:25], v[130:133], v[168:171], v[22:25]
	v_mfma_f32_16x16x32_bf16 v[18:21], v[192:195], v[168:171], v[18:21]
	v_mfma_f32_16x16x32_bf16 v[30:33], v[160:163], v[164:167], v[30:33]
	v_mfma_f32_16x16x32_bf16 v[26:29], v[196:199], v[164:167], v[26:29]
	v_mfma_f32_16x16x32_bf16 v[22:25], v[160:163], v[172:175], v[22:25]
	v_mfma_f32_16x16x32_bf16 v[18:21], v[196:199], v[172:175], v[18:21]
	v_mfma_f32_16x16x32_bf16 v[14:17], v[130:133], v[176:179], v[14:17]
	v_mfma_f32_16x16x32_bf16 v[10:13], v[192:195], v[176:179], v[10:13]
	v_mfma_f32_16x16x32_bf16 v[6:9], v[130:133], v[184:187], v[6:9]
	v_mfma_f32_16x16x32_bf16 v[2:5], v[192:195], v[184:187], v[2:5]
	v_mfma_f32_16x16x32_bf16 v[14:17], v[160:163], v[180:183], v[14:17]
	v_mfma_f32_16x16x32_bf16 v[10:13], v[196:199], v[180:183], v[10:13]
	v_mfma_f32_16x16x32_bf16 v[6:9], v[160:163], v[188:191], v[6:9]
	v_mfma_f32_16x16x32_bf16 v[2:5], v[196:199], v[188:191], v[2:5]
.Lwin_skip2:
	s_setprio 0
	s_barrier
	ds_read_b128 v[152:155], v150 offset:32768
	ds_read_b128 v[156:159], v150 offset:33792
	ds_read_b128 v[160:163], v150 offset:34816
	ds_read_b128 v[164:167], v150 offset:35840
	ds_read_b128 v[168:171], v0 offset:32768
	ds_read_b128 v[172:175], v0 offset:33792
	ds_read_b128 v[176:179], v0 offset:34816
	ds_read_b128 v[180:183], v0 offset:35840
	ds_read_b128 v[184:187], v0 offset:36864
	ds_read_b128 v[188:191], v0 offset:37888
	ds_read_b128 v[192:195], v0 offset:38912
	ds_read_b128 v[196:199], v0 offset:39936
	s_waitcnt vmcnt(2)
	s_barrier
	s_waitcnt lgkmcnt(0)
	s_setprio 1
	s_waitcnt lgkmcnt(0)
	v_mfma_f32_16x16x32_bf16 v[126:129], v[152:155], v[168:171], v[126:129]
	v_mfma_f32_16x16x32_bf16 v[122:125], v[160:163], v[168:171], v[122:125]
	v_mfma_f32_16x16x32_bf16 v[118:121], v[152:155], v[176:179], v[118:121]
	v_mfma_f32_16x16x32_bf16 v[114:117], v[160:163], v[176:179], v[114:117]
	v_mfma_f32_16x16x32_bf16 v[110:113], v[152:155], v[184:187], v[110:113]
	v_mfma_f32_16x16x32_bf16 v[106:109], v[160:163], v[184:187], v[106:109]
	v_mfma_f32_16x16x32_bf16 v[102:105], v[152:155], v[192:195], v[102:105]
	v_mfma_f32_16x16x32_bf16 v[98:101], v[160:163], v[192:195], v[98:101]
	v_mfma_f32_16x16x32_bf16 v[142:145], v[156:159], v[172:175], v[126:129]
	v_mfma_f32_16x16x32_bf16 v[138:141], v[164:167], v[172:175], v[122:125]
	v_mfma_f32_16x16x32_bf16 v[134:137], v[156:159], v[180:183], v[118:121]
	v_mfma_f32_16x16x32_bf16 v[130:133], v[164:167], v[180:183], v[114:117]
	v_mfma_f32_16x16x32_bf16 v[126:129], v[156:159], v[188:191], v[110:113]
	v_mfma_f32_16x16x32_bf16 v[122:125], v[164:167], v[188:191], v[106:109]
	v_mfma_f32_16x16x32_bf16 v[118:121], v[156:159], v[196:199], v[102:105]
	v_mfma_f32_16x16x32_bf16 v[114:117], v[164:167], v[196:199], v[98:101]
	s_setprio 0
	s_barrier
	ds_read_b128 v[200:203], v150 offset:49152
	ds_read_b128 v[204:207], v150 offset:50176
	ds_read_b128 v[208:211], v150 offset:51200
	ds_read_b128 v[148:151], v150 offset:52224
	s_waitcnt vmcnt(0)
	s_barrier
	s_waitcnt lgkmcnt(0)
	s_setprio 1
	s_waitcnt lgkmcnt(0)
	s_cmp_lg_u32 s98, 0
	s_cbranch_scc1 .Lwin_skip1
	v_mfma_f32_16x16x32_bf16 v[94:97], v[200:203], v[168:171], v[94:97]
	v_mfma_f32_16x16x32_bf16 v[90:93], v[208:211], v[168:171], v[90:93]
	v_mfma_f32_16x16x32_bf16 v[86:89], v[200:203], v[176:179], v[86:89]
	v_mfma_f32_16x16x32_bf16 v[82:85], v[208:211], v[176:179], v[82:85]
	v_mfma_f32_16x16x32_bf16 v[78:81], v[200:203], v[184:187], v[78:81]
	v_mfma_f32_16x16x32_bf16 v[74:77], v[208:211], v[184:187], v[74:77]
	v_mfma_f32_16x16x32_bf16 v[70:73], v[200:203], v[192:195], v[70:73]
	v_mfma_f32_16x16x32_bf16 v[66:69], v[208:211], v[192:195], v[66:69]
	v_mfma_f32_16x16x32_bf16 v[110:113], v[204:207], v[172:175], v[94:97]
	v_mfma_f32_16x16x32_bf16 v[106:109], v[148:151], v[172:175], v[90:93]
	v_mfma_f32_16x16x32_bf16 v[102:105], v[204:207], v[180:183], v[86:89]
	v_mfma_f32_16x16x32_bf16 v[98:101], v[148:151], v[180:183], v[82:85]
	v_mfma_f32_16x16x32_bf16 v[94:97], v[204:207], v[188:191], v[78:81]
	v_mfma_f32_16x16x32_bf16 v[90:93], v[148:151], v[188:191], v[74:77]
	v_mfma_f32_16x16x32_bf16 v[86:89], v[204:207], v[196:199], v[70:73]
	v_mfma_f32_16x16x32_bf16 v[82:85], v[148:151], v[196:199], v[66:69]
.Lwin_skip1:
	s_setprio 0
	s_barrier
	ds_read_b128 v[168:171], v0 offset:49152
	ds_read_b128 v[172:175], v0 offset:50176
	ds_read_b128 v[176:179], v0 offset:51200
	ds_read_b128 v[180:183], v0 offset:52224
	ds_read_b128 v[184:187], v0 offset:53248
	ds_read_b128 v[188:191], v0 offset:54272
	ds_read_b128 v[192:195], v0 offset:55296
	ds_read_b128 v[196:199], v0 offset:56320
	s_barrier
	s_waitcnt lgkmcnt(0)
	s_setprio 1
	s_waitcnt lgkmcnt(0)
	v_mfma_f32_16x16x32_bf16 v[62:65], v[152:155], v[168:171], v[62:65]
	v_mfma_f32_16x16x32_bf16 v[58:61], v[160:163], v[168:171], v[58:61]
	v_mfma_f32_16x16x32_bf16 v[54:57], v[152:155], v[176:179], v[54:57]
	v_mfma_f32_16x16x32_bf16 v[50:53], v[160:163], v[176:179], v[50:53]
	v_mfma_f32_16x16x32_bf16 v[46:49], v[152:155], v[184:187], v[46:49]
	v_mfma_f32_16x16x32_bf16 v[42:45], v[160:163], v[184:187], v[42:45]
	v_mfma_f32_16x16x32_bf16 v[38:41], v[152:155], v[192:195], v[38:41]
	v_mfma_f32_16x16x32_bf16 v[34:37], v[160:163], v[192:195], v[34:37]
	v_mfma_f32_16x16x32_bf16 v[78:81], v[156:159], v[172:175], v[62:65]
	v_mfma_f32_16x16x32_bf16 v[74:77], v[164:167], v[172:175], v[58:61]
	v_mfma_f32_16x16x32_bf16 v[70:73], v[156:159], v[180:183], v[54:57]
	v_mfma_f32_16x16x32_bf16 v[66:69], v[164:167], v[180:183], v[50:53]
	v_mfma_f32_16x16x32_bf16 v[62:65], v[156:159], v[188:191], v[46:49]
	v_mfma_f32_16x16x32_bf16 v[58:61], v[164:167], v[188:191], v[42:45]
	v_mfma_f32_16x16x32_bf16 v[54:57], v[156:159], v[196:199], v[38:41]
	v_mfma_f32_16x16x32_bf16 v[50:53], v[164:167], v[196:199], v[34:37]
	s_setprio 0
	s_setprio 1
	s_cmp_lg_u32 s98, 0
	s_cbranch_scc1 .Lwin_skip0
	v_mfma_f32_16x16x32_bf16 v[30:33], v[200:203], v[168:171], v[30:33]
	v_mfma_f32_16x16x32_bf16 v[26:29], v[208:211], v[168:171], v[26:29]
	v_mfma_f32_16x16x32_bf16 v[22:25], v[200:203], v[176:179], v[22:25]
	v_mfma_f32_16x16x32_bf16 v[18:21], v[208:211], v[176:179], v[18:21]
	v_mfma_f32_16x16x32_bf16 v[14:17], v[200:203], v[184:187], v[14:17]
	v_mfma_f32_16x16x32_bf16 v[10:13], v[208:211], v[184:187], v[10:13]
	v_mfma_f32_16x16x32_bf16 v[6:9], v[200:203], v[192:195], v[6:9]
	v_mfma_f32_16x16x32_bf16 v[2:5], v[208:211], v[192:195], v[2:5]
	v_mfma_f32_16x16x32_bf16 v[46:49], v[204:207], v[172:175], v[30:33]
	v_mfma_f32_16x16x32_bf16 v[42:45], v[148:151], v[172:175], v[26:29]
	v_mfma_f32_16x16x32_bf16 v[38:41], v[204:207], v[180:183], v[22:25]
	v_mfma_f32_16x16x32_bf16 v[34:37], v[148:151], v[180:183], v[18:21]
	v_mfma_f32_16x16x32_bf16 v[30:33], v[204:207], v[188:191], v[14:17]
	v_mfma_f32_16x16x32_bf16 v[26:29], v[148:151], v[188:191], v[10:13]
	v_mfma_f32_16x16x32_bf16 v[22:25], v[204:207], v[196:199], v[6:9]
	v_mfma_f32_16x16x32_bf16 v[18:21], v[148:151], v[196:199], v[2:5]
.Lwin_skip0:
	s_setprio 0
	s_movk_i32 s0, 0x100
	v_cmp_gt_u32_e32 vcc, s0, v146
	s_barrier
	s_and_saveexec_b64 s[0:1], vcc
	s_cbranch_execz .LBB0_364
	s_barrier

.LBB0_545:
	s_waitcnt vmcnt(0)
	s_barrier
	v_readlane_b32 s0, v254, 54
	s_cmp_lg_u32 s0, 0
	s_cbranch_scc1 .Lxb_join
	v_readlane_b32 s30, v253, 1
	v_readlane_b32 s31, v253, 2
	v_readlane_b32 s22, v254, 46
	v_readlane_b32 s23, v255, 12
	v_mov_b32_e32 v4, 0
	s_cmp_lg_u32 s23, 0
	s_cbranch_scc1 .Lxb_go
	v_readlane_b32 s18, v253, 5
	v_readlane_b32 s19, v253, 6
	s_load_dwordx2 s[8:9], s[18:19], 0x0
	s_load_dword s20, s[18:19], 0x8
	s_add_u32 s36, s30, 0x400
	s_addc_u32 s37, s31, 0
	s_lshr_b32 s21, s22, 8
	s_mov_b64 exec, 0xffff
	v_mbcnt_lo_u32_b32 v3, -1, 0
	v_lshlrev_b32_e32 v3, 8, v3
	s_waitcnt lgkmcnt(0)
	s_mul_i32 s8, s9, s8
	s_mul_i32 s8, s8, s20
	s_mov_b32 s20, 0
.Lxb_cnt:
	global_load_dword v5, v3, s[36:37] sc1
	s_add_i32 s20, s20, 1
	s_mov_b32 s9, 0
	s_waitcnt vmcnt(0)
	v_readlane_b32 s24, v5, 0
	s_add_i32 s9, s9, s24
	v_readlane_b32 s24, v5, 1
	s_add_i32 s9, s9, s24
	v_readlane_b32 s24, v5, 2
	s_add_i32 s9, s9, s24
	v_readlane_b32 s24, v5, 3
	s_add_i32 s9, s9, s24
	v_readlane_b32 s24, v5, 4
	s_add_i32 s9, s9, s24
	v_readlane_b32 s24, v5, 5
	s_add_i32 s9, s9, s24
	v_readlane_b32 s24, v5, 6
	s_add_i32 s9, s9, s24
	v_readlane_b32 s24, v5, 7
	s_add_i32 s9, s9, s24
	v_readlane_b32 s24, v5, 8
	s_add_i32 s9, s9, s24
	v_readlane_b32 s24, v5, 9
	s_add_i32 s9, s9, s24
	v_readlane_b32 s24, v5, 10
	s_add_i32 s9, s9, s24
	v_readlane_b32 s24, v5, 11
	s_add_i32 s9, s9, s24
	v_readlane_b32 s24, v5, 12
	s_add_i32 s9, s9, s24
	v_readlane_b32 s24, v5, 13
	s_add_i32 s9, s9, s24
	v_readlane_b32 s24, v5, 14
	s_add_i32 s9, s9, s24
	v_readlane_b32 s24, v5, 15
	s_add_i32 s9, s9, s24
	s_cmp_eq_u32 s9, s8
	s_cbranch_scc1 .Lxb_cnt_done
	s_sleep 1
	s_cmp_lt_u32 s20, 0x20000
	s_cbranch_scc1 .Lxb_cnt
.Lxb_cnt_done:
	v_cmp_ne_u32_e32 vcc, 0, v5
	s_nop 3
	v_readlane_b32 s24, v5, s21
	s_bcnt1_i32_b64 s25, vcc
	s_max_u32 s24, s24, 1
	s_max_u32 s25, s25, 1
	v_writelane_b32 v255, s24, 13
	v_writelane_b32 v255, s25, 14
.Lxb_go:
	s_mov_b64 exec, 1
	v_readlane_b32 s24, v255, 13
	v_readlane_b32 s25, v255, 14
	s_add_u32 s36, s30, 0x1400
	s_addc_u32 s37, s31, 0
	s_add_u32 s36, s36, s22
	s_addc_u32 s37, s37, 0
	s_add_u32 s38, s30, 0x2400
	s_addc_u32 s39, s31, 0
	s_add_i32 s21, s23, 1
	v_writelane_b32 v255, s21, 12
	s_mul_i32 s24, s24, s21
	s_mul_i32 s25, s25, s21
	v_mov_b32_e32 v2, 1
	global_atomic_add v3, v4, v2, s[36:37] sc0
	s_waitcnt vmcnt(0)
	v_readfirstlane_b32 s21, v3
	s_add_i32 s21, s21, 1
	s_cmp_lg_u32 s21, s24
	s_cbranch_scc1 .Lxb_wait
	buffer_wbl2 sc1
	s_add_u32 s36, s30, 0x3400
	s_addc_u32 s37, s31, 0
	s_waitcnt vmcnt(0)
	global_atomic_add v3, v4, v2, s[36:37] sc0
	s_waitcnt vmcnt(0)
	v_readfirstlane_b32 s21, v3
	s_add_i32 s21, s21, 1
	s_cmp_lg_u32 s21, s25
	s_cbranch_scc1 .Lxb_wait
	s_mov_b64 exec, 0xffff
	v_mbcnt_lo_u32_b32 v3, -1, 0
	v_mov_b32_e32 v2, 1
	v_lshlrev_b32_e32 v3, 8, v3
	global_atomic_add v3, v2, s[38:39]
	s_mov_b64 exec, 1
	s_branch .Lxb_acq
.Lxb_wait:
	s_add_u32 s38, s38, s22
	s_addc_u32 s39, s39, 0
	s_mov_b32 s20, 0
.Lxb_spin:
	s_sleep 1
	global_load_dword v3, v4, s[38:39] sc1
	s_add_i32 s20, s20, 1
	s_waitcnt vmcnt(0)
	v_readfirstlane_b32 s21, v3
	s_cmp_lg_u32 s21, s23
	s_cbranch_scc1 .Lxb_acq
	s_cmp_lt_u32 s20, 0x20000
	s_cbranch_scc1 .Lxb_spin
.Lxb_acq:
	buffer_inv sc1
	s_mov_b64 exec, -1
.Lxb_join:
	s_getpc_b64 s[98:99]
